# phase 5: touch the item's 64 KB recurrent-state lines at item start so the later operand loads hit L2
# baseline (speedup 1.0000x reference)
.LBB0_311:
	v_mov_b32_e32 v180, v205
	v_lshlrev_b32_e32 v208, 7, v205
	s_lshl_b32 s98, s84, 16
	s_add_u32 s98, s98, 0x15800000
	v_add_u32_e32 v208, s98, v208
	v_add_u32_e32 v210, 0x8000, v208
	global_load_dword v209, v208, s[26:27]
	global_load_dword v211, v210, s[26:27]
	s_and_b32 s0, s3, 0xffffffc0
	v_ashrrev_i32_e32 v179, 2, v180
	v_and_b32_e32 v17, 0xffffffe0, v179
	v_and_b32_e32 v5, 0x7f, v180
	v_lshrrev_b32_e32 v0, 5, v179
	v_add_u32_e32 v2, s0, v17
	s_and_b32 s1, s84, 3
	v_mul_lo_u32 v0, v0, s48
	v_lshlrev_b32_e32 v6, 1, v5
	v_ashrrev_i32_e32 v3, 31, v2
	s_lshl_b32 s6, s1, 8
	s_lshl_b32 s17, s1, 9
	v_or_b32_e32 v4, v0, v6
	v_mad_i64_i32 v[0:1], s[0:1], v2, s49, 0
	v_lshlrev_b64 v[2:3], 11, v[2:3]
	v_lshlrev_b32_e32 v5, 2, v5
	v_or3_b32 v0, v0, s6, v6
	v_or3_b32 v2, v2, s17, v5
	s_movk_i32 s6, 0x1400
